# v22 = v18 + grid-barrier master poll: the 16 arrival-counter loads issued back-to-back with one vmcnt(0) (were serialised by a wait after each), in all 9 barrier instances
# speedup vs baseline: 1.0093x; 1.0090x over previous
.LBB0_515:
	v_readlane_b32 s2, v254, 0
	v_readlane_b32 s3, v254, 1
	s_mov_b64 s[18:19], -1
	s_waitcnt lgkmcnt(0)
	s_nop 2
	global_load_dword v0, v195, s[2:3] sc1
	v_readlane_b32 s2, v254, 2
	v_readlane_b32 s3, v254, 3
	s_nop 4
	global_load_dword v1, v195, s[2:3] sc1
	v_readlane_b32 s2, v254, 4
	v_readlane_b32 s3, v254, 5
	s_nop 4
	global_load_dword v2, v195, s[2:3] sc1
	v_readlane_b32 s2, v254, 6
	v_readlane_b32 s3, v254, 7
	s_nop 4
	global_load_dword v3, v195, s[2:3] sc1
	v_readlane_b32 s2, v254, 8
	v_readlane_b32 s3, v254, 9
	s_nop 4
	global_load_dword v4, v195, s[2:3] sc1
	v_readlane_b32 s2, v254, 10
	v_readlane_b32 s3, v254, 11
	s_nop 4
	global_load_dword v5, v195, s[2:3] sc1
	v_readlane_b32 s2, v254, 12
	v_readlane_b32 s3, v254, 13
	s_nop 4
	global_load_dword v6, v195, s[2:3] sc1
	v_readlane_b32 s2, v254, 14
	v_readlane_b32 s3, v254, 15
	s_nop 4
	global_load_dword v7, v195, s[2:3] sc1
	v_readlane_b32 s2, v254, 16
	v_readlane_b32 s3, v254, 17
	s_nop 4
	global_load_dword v8, v195, s[2:3] sc1
	v_readlane_b32 s2, v254, 18
	v_readlane_b32 s3, v254, 19
	s_nop 4
	global_load_dword v9, v195, s[2:3] sc1
	v_readlane_b32 s2, v254, 20
	v_readlane_b32 s3, v254, 21
	s_nop 4
	global_load_dword v10, v195, s[2:3] sc1
	v_readlane_b32 s2, v254, 22
	v_readlane_b32 s3, v254, 23
	s_nop 4
	global_load_dword v11, v195, s[2:3] sc1
	v_readlane_b32 s2, v254, 24
	v_readlane_b32 s3, v254, 25
	s_nop 4
	global_load_dword v12, v195, s[2:3] sc1
	v_readlane_b32 s2, v254, 26
	v_readlane_b32 s3, v254, 27
	s_nop 4
	global_load_dword v13, v195, s[2:3] sc1
	v_readlane_b32 s2, v254, 28
	v_readlane_b32 s3, v254, 29
	s_nop 4
	global_load_dword v14, v195, s[2:3] sc1
	v_readlane_b32 s2, v254, 30
	v_readlane_b32 s3, v254, 31
	s_nop 4
	global_load_dword v15, v195, s[2:3] sc1
	s_mov_b64 s[2:3], -1
	s_waitcnt vmcnt(0)
	v_add_u32_e32 v16, v1, v0
	v_add_u32_e32 v16, v16, v2
	v_add_u32_e32 v16, v16, v3
	v_add_u32_e32 v16, v16, v4
	v_add_u32_e32 v16, v16, v5
	v_add_u32_e32 v16, v16, v6
	v_add_u32_e32 v16, v16, v7
	v_add_u32_e32 v16, v16, v8
	v_add_u32_e32 v16, v16, v9
	v_add_u32_e32 v16, v16, v10
	v_add_u32_e32 v16, v16, v11
	v_add_u32_e32 v16, v16, v12
	v_add_u32_e32 v16, v16, v13
	v_add_u32_e32 v16, v16, v14
	v_add_u32_e32 v16, v16, v15
	v_cmp_eq_u32_e32 vcc, s95, v16
	s_cbranch_vccnz .LBB0_514
	s_and_b32 s2, s4, 0xff
	s_cmp_eq_u32 s2, 0
	s_mov_b64 s[2:3], -1
	s_mov_b64 s[20:21], -1
	s_sleep 1
	s_cbranch_scc1 .LBB0_519
	s_and_b64 vcc, exec, s[20:21]
	s_cbranch_vccz .LBB0_514
